# K-up epilogue: lane-permutation constant now computed inside the exec region that uses it (was computed before the exec flip and only correct via the earlier Q-up epilogue's value)
# baseline (speedup 1.0000x reference)
; template <int EPI, int TI>
; __device__ __forceinline__ void gemm_epilogue(const WS& ws, const f32x4 (&acc)[4][TI], const float (&rs)[TI], int tok0, int n0,
;                                               int wm, int wn, int lr, int lq, bool dry) {
;     ...
;     if (!isv) {
; #pragma unroll
;       for (int ni = 0; ni < 4; ++ni)
; #pragma unroll
;         for (int ti = 0; ti < TI; ++ti) {
;           const f32x4 v = scale4(acc[ni][ti], rs[ti]);
;           u32x2 pk; pk.x = cvt_pk_bf16(v[0], v[1]); pk.y = cvt_pk_bf16(v[2], v[3]);
;           if (okr(ti)) *(u32x2*)(ws.KN + (size_t)tokr(ti) * 1024 + hd * 64 + ni * 16 + 4 * lq) = pk;
;         }
.LBB0_772:
	s_andn2_saveexec_b64 s[4:5], s[4:5]
	s_cbranch_execz .LBB0_774
	v_mbcnt_lo_u32_b32 v250, -1, 0
	v_mbcnt_hi_u32_b32 v250, -1, v250
	v_and_b32_e32 v251, 3, v250
	v_lshrrev_b32_e32 v250, 2, v250
	v_lshl_add_u32 v250, v251, 4, v250
	v_lshlrev_b32_e32 v250, 2, v250
	v_lshlrev_b32_e32 v132, 6, v13
	s_waitcnt lgkmcnt(1)
	v_mov_b32_e32 v13, v128
	v_ashrrev_i32_e32 v131, 31, v130
	v_mul_f32_e32 v110, v110, v13
	v_mul_f32_e32 v111, v111, v13
	v_mul_f32_e32 v112, v112, v13
	v_mul_f32_e32 v13, v113, v13
	v_ashrrev_i32_e32 v133, 31, v132
	v_cvt_pk_bf16_f32 v110, v110, v111
	v_cvt_pk_bf16_f32 v111, v112, v13
	v_lshlrev_b64 v[112:113], 11, v[130:131]
	v_lshl_add_u64 v[112:113], s[46:47], 0, v[112:113]
	v_lshl_add_u64 v[112:113], v[132:133], 1, v[112:113]
	v_mov_b32_e32 v121, v12
	v_lshl_add_u64 v[112:113], v[112:113], 0, v[120:121]
	v_mov_b32_e32 v13, v129
	ds_bpermute_b32 v242, v250, v112
	ds_bpermute_b32 v243, v250, v113
	ds_bpermute_b32 v252, v250, v110
	ds_bpermute_b32 v253, v250, v111
	s_mov_b32 s3, 0x8000
	v_mul_f32_e32 v102, v102, v13
	v_mul_f32_e32 v103, v103, v13
	v_mul_f32_e32 v104, v104, v13
	v_mul_f32_e32 v13, v105, v13
	v_add_co_u32_e32 v110, vcc, s3, v112
	v_cvt_pk_bf16_f32 v102, v102, v103
	v_cvt_pk_bf16_f32 v103, v104, v13
	v_addc_co_u32_e32 v111, vcc, 0, v113, vcc
	s_waitcnt lgkmcnt(0)
	v_mov_b32_e32 v13, v126
	ds_bpermute_b32 v244, v250, v110
	ds_bpermute_b32 v245, v250, v111
	ds_bpermute_b32 v254, v250, v102
	ds_bpermute_b32 v255, v250, v103
	s_waitcnt lgkmcnt(4)
	global_store_dwordx2 v[242:243], v[252:253], off
	v_add_co_u32_e32 v102, vcc, s82, v112
	v_mul_f32_e32 v86, v86, v13
	v_mul_f32_e32 v87, v87, v13
	v_mul_f32_e32 v88, v88, v13
	v_mul_f32_e32 v13, v89, v13
	v_addc_co_u32_e32 v103, vcc, 0, v113, vcc
	v_cvt_pk_bf16_f32 v86, v86, v87
	v_cvt_pk_bf16_f32 v87, v88, v13
	v_mov_b32_e32 v13, v127
	ds_bpermute_b32 v246, v250, v102
	ds_bpermute_b32 v247, v250, v103
	ds_bpermute_b32 v252, v250, v86
	ds_bpermute_b32 v253, v250, v87
	s_waitcnt lgkmcnt(4)
	global_store_dwordx2 v[244:245], v[254:255], off
	s_mov_b32 s3, 0x18000
	v_mul_f32_e32 v70, v70, v13
	v_mul_f32_e32 v71, v71, v13
	v_mul_f32_e32 v72, v72, v13
	v_mul_f32_e32 v13, v73, v13
	v_add_co_u32_e32 v86, vcc, s3, v112
	v_cvt_pk_bf16_f32 v70, v70, v71
	v_cvt_pk_bf16_f32 v71, v72, v13
	v_addc_co_u32_e32 v87, vcc, 0, v113, vcc
	v_mov_b32_e32 v13, v128
	ds_bpermute_b32 v248, v250, v86
	ds_bpermute_b32 v249, v250, v87
	ds_bpermute_b32 v254, v250, v70
	ds_bpermute_b32 v255, v250, v71
	s_waitcnt lgkmcnt(4)
	global_store_dwordx2 v[246:247], v[252:253], off
	s_mov_b64 s[10:11], 0x8000
	v_mul_f32_e32 v70, v106, v13
	v_mul_f32_e32 v71, v107, v13
	v_mul_f32_e32 v86, v108, v13
	v_mul_f32_e32 v13, v109, v13
	v_lshl_add_u64 v[104:105], v[112:113], 0, s[10:11]
	v_cvt_pk_bf16_f32 v70, v70, v71
	v_cvt_pk_bf16_f32 v71, v86, v13
	v_mov_b32_e32 v13, v129
	ds_bpermute_b32 v252, v250, v70
	ds_bpermute_b32 v253, v250, v71
	s_waitcnt lgkmcnt(2)
	global_store_dwordx2 v[248:249], v[254:255], off
	s_mov_b64 s[10:11], 0x10000
	v_mul_f32_e32 v70, v94, v13
	v_mul_f32_e32 v71, v95, v13
	v_mul_f32_e32 v86, v96, v13
	v_mul_f32_e32 v13, v97, v13
	v_lshl_add_u64 v[88:89], v[112:113], 0, s[10:11]
	v_cvt_pk_bf16_f32 v70, v70, v71
	v_cvt_pk_bf16_f32 v71, v86, v13
	v_mov_b32_e32 v13, v126
	ds_bpermute_b32 v248, v250, v104
	ds_bpermute_b32 v249, v250, v105
	ds_bpermute_b32 v254, v250, v70
	ds_bpermute_b32 v255, v250, v71
	s_waitcnt lgkmcnt(4)
	global_store_dwordx2 v[242:243], v[252:253], off offset:32
	s_mov_b64 s[10:11], 0x18000
	v_mul_f32_e32 v70, v78, v13
	v_mul_f32_e32 v71, v79, v13
	v_mul_f32_e32 v78, v80, v13
	v_mul_f32_e32 v13, v81, v13
	v_lshl_add_u64 v[72:73], v[112:113], 0, s[10:11]
	v_cvt_pk_bf16_f32 v70, v70, v71
	v_cvt_pk_bf16_f32 v71, v78, v13
	v_mov_b32_e32 v13, v127
	ds_bpermute_b32 v242, v250, v88
	ds_bpermute_b32 v243, v250, v89
	ds_bpermute_b32 v252, v250, v70
	ds_bpermute_b32 v253, v250, v71
	s_waitcnt lgkmcnt(4)
; template <int EPI, int TI>
; __device__ __forceinline__ void gemm_epilogue(const WS& ws, const f32x4 (&acc)[4][TI], const float (&rs)[TI], int tok0, int n0,
;                                               int wm, int wn, int lr, int lq, bool dry) {
;     ...
;     if (!isv) {
; #pragma unroll
;       for (int ni = 0; ni < 4; ++ni)
; #pragma unroll
;         for (int ti = 0; ti < TI; ++ti) {
;           const f32x4 v = scale4(acc[ni][ti], rs[ti]);
;           u32x2 pk; pk.x = cvt_pk_bf16(v[0], v[1]); pk.y = cvt_pk_bf16(v[2], v[3]);
;           if (okr(ti)) *(u32x2*)(ws.KN + (size_t)tokr(ti) * 1024 + hd * 64 + ni * 16 + 4 * lq) = pk;
;         }
	global_store_dwordx2 v[248:249], v[254:255], off offset:32
	s_nop 0
	v_mul_f32_e32 v62, v62, v13
	v_mul_f32_e32 v63, v63, v13
	v_mul_f32_e32 v64, v64, v13
	v_mul_f32_e32 v13, v65, v13
	s_nop 0
	v_cvt_pk_bf16_f32 v62, v62, v63
	v_cvt_pk_bf16_f32 v63, v64, v13
	v_mov_b32_e32 v13, v128
	ds_bpermute_b32 v244, v250, v72
	ds_bpermute_b32 v245, v250, v73
	ds_bpermute_b32 v254, v250, v62
	ds_bpermute_b32 v255, v250, v63
	s_waitcnt lgkmcnt(4)
	global_store_dwordx2 v[242:243], v[252:253], off offset:32
	s_nop 0
	v_mul_f32_e32 v62, v98, v13
	v_mul_f32_e32 v63, v99, v13
	v_mul_f32_e32 v64, v100, v13
	v_mul_f32_e32 v13, v101, v13
	s_nop 0
	v_cvt_pk_bf16_f32 v62, v62, v63
	v_cvt_pk_bf16_f32 v63, v64, v13
	v_mov_b32_e32 v13, v129
	ds_bpermute_b32 v246, v250, v112
	ds_bpermute_b32 v247, v250, v113
	ds_bpermute_b32 v252, v250, v62
	ds_bpermute_b32 v253, v250, v63
	s_waitcnt lgkmcnt(4)
	global_store_dwordx2 v[244:245], v[254:255], off offset:32
	s_nop 0
	v_mul_f32_e32 v62, v82, v13
	v_mul_f32_e32 v63, v83, v13
	v_mul_f32_e32 v64, v84, v13
	v_mul_f32_e32 v13, v85, v13
	s_nop 0
	v_cvt_pk_bf16_f32 v62, v62, v63
	v_cvt_pk_bf16_f32 v63, v64, v13
	v_mov_b32_e32 v13, v126
	ds_bpermute_b32 v254, v250, v62
	ds_bpermute_b32 v255, v250, v63
	s_waitcnt lgkmcnt(2)
	global_store_dwordx2 v[246:247], v[252:253], off offset:64
	s_nop 0
	v_mul_f32_e32 v62, v66, v13
	v_mul_f32_e32 v63, v67, v13
	v_mul_f32_e32 v64, v68, v13
	v_mul_f32_e32 v13, v69, v13
	s_nop 0
	v_cvt_pk_bf16_f32 v62, v62, v63
	v_cvt_pk_bf16_f32 v63, v64, v13
	v_mov_b32_e32 v13, v127
	ds_bpermute_b32 v252, v250, v62
	ds_bpermute_b32 v253, v250, v63
	s_waitcnt lgkmcnt(2)
	global_store_dwordx2 v[248:249], v[254:255], off offset:64
	s_nop 0
	v_mul_f32_e32 v54, v54, v13
	v_mul_f32_e32 v55, v55, v13
	v_mul_f32_e32 v56, v56, v13
	v_mul_f32_e32 v13, v57, v13
	s_nop 0
	v_cvt_pk_bf16_f32 v54, v54, v55
	v_cvt_pk_bf16_f32 v55, v56, v13
	ds_bpermute_b32 v254, v250, v54
	ds_bpermute_b32 v255, v250, v55
	s_waitcnt lgkmcnt(2)
	global_store_dwordx2 v[242:243], v[252:253], off offset:64
	s_nop 0
	v_mul_f32_e32 v13, v90, v128
	v_mul_f32_e32 v54, v91, v128
	v_mul_f32_e32 v55, v92, v128
	v_mul_f32_e32 v56, v93, v128
	s_nop 0
	v_cvt_pk_bf16_f32 v54, v13, v54
	v_cvt_pk_bf16_f32 v55, v55, v56
	ds_bpermute_b32 v252, v250, v54
	ds_bpermute_b32 v253, v250, v55
	s_waitcnt lgkmcnt(2)
	global_store_dwordx2 v[244:245], v[254:255], off offset:64
	s_nop 0
	v_mul_f32_e32 v13, v74, v129
	v_mul_f32_e32 v54, v75, v129
	v_mul_f32_e32 v55, v76, v129
	v_mul_f32_e32 v56, v77, v129
	s_nop 0
	v_cvt_pk_bf16_f32 v54, v13, v54
	v_cvt_pk_bf16_f32 v55, v55, v56
	ds_bpermute_b32 v254, v250, v54
	ds_bpermute_b32 v255, v250, v55
	s_waitcnt lgkmcnt(2)
	global_store_dwordx2 v[246:247], v[252:253], off offset:96
	s_nop 0
	v_mul_f32_e32 v13, v58, v126
	v_mul_f32_e32 v54, v59, v126
	v_mul_f32_e32 v55, v60, v126
	v_mul_f32_e32 v56, v61, v126
	s_nop 0
	v_cvt_pk_bf16_f32 v54, v13, v54
	v_cvt_pk_bf16_f32 v55, v55, v56
	ds_bpermute_b32 v252, v250, v54
	ds_bpermute_b32 v253, v250, v55
	s_waitcnt lgkmcnt(2)
	global_store_dwordx2 v[248:249], v[254:255], off offset:96
	s_nop 0
	v_mul_f32_e32 v13, v50, v127
	v_mul_f32_e32 v50, v51, v127
	v_mul_f32_e32 v51, v52, v127
	v_mul_f32_e32 v52, v53, v127
	s_nop 0
	v_cvt_pk_bf16_f32 v50, v13, v50
	v_cvt_pk_bf16_f32 v51, v51, v52
	ds_bpermute_b32 v254, v250, v50
	ds_bpermute_b32 v255, v250, v51
	s_waitcnt lgkmcnt(2)
	global_store_dwordx2 v[242:243], v[252:253], off offset:96
	s_waitcnt lgkmcnt(0)
	global_store_dwordx2 v[244:245], v[254:255], off offset:96
